# K-norm: gain vector hoisted out of the row loop, next row prefetched; P1 RMSNorm row loads batched (32 in flight)
# speedup vs baseline: 1.1061x; 1.0031x over previous
.LBB0_212:
	v_mov_b32_e32 v4, v1
	v_readlane_b32 s0, v252, 30
	v_ashrrev_i32_e32 v2, 6, v4
	s_lshl_b32 s40, s24, 7
	v_add_u32_e32 v6, s0, v2
	s_movk_i32 s0, 0x4800
	s_mov_b32 s41, s43
	v_cmp_gt_i32_e32 vcc, s0, v6
	s_and_saveexec_b64 s[0:1], vcc
	s_cbranch_execz .LBB0_215
	v_readlane_b32 s52, v252, 12
	v_readlane_b32 s60, v252, 20
	v_readlane_b32 s61, v252, 21
	v_readlane_b32 s62, v252, 22
	v_readlane_b32 s63, v252, 23
	v_readlane_b32 s64, v252, 24
	v_readlane_b32 s65, v252, 25
	s_mov_b32 s2, s25
	s_mov_b64 s[20:21], s[60:61]
	s_lshl_b64 s[4:5], s[40:41], 2
	s_mov_b64 s[22:23], s[62:63]
	s_mov_b64 s[24:25], s[64:65]
	v_readlane_b32 s24, v250, 2
	s_add_u32 s4, s22, s4
	v_lshlrev_b32_e32 v2, 6, v4
	v_cmp_lt_i32_e32 vcc, v240, v234
	v_readlane_b32 s25, v250, 3
	s_addc_u32 s5, s23, s5
	v_and_b32_e32 v194, 0x1c0, v2
	v_cndmask_b32_e32 v5, v233, v240, vcc
	v_cmp_lt_i32_e32 vcc, v239, v234
	s_mov_b32 s25, s2
	v_lshl_add_u64 v[2:3], s[4:5], 0, v[194:195]
	v_lshlrev_b32_e32 v7, 2, v5
	v_cndmask_b32_e32 v5, v233, v239, vcc
	v_cmp_lt_i32_e32 vcc, v238, v234
	v_mad_i64_i32 v[10:11], s[4:5], v6, s37, 0
	v_and_b32_e32 v4, 63, v4
	v_readlane_b32 s2, v251, 54
	v_readlane_b32 s66, v252, 26
	v_readlane_b32 s64, v250, 8
	v_readlane_b32 s14, v252, 51
	v_readlane_b32 s22, v250, 19
	v_lshlrev_b32_e32 v8, 2, v5
	v_cndmask_b32_e32 v5, v233, v238, vcc
	v_lshl_or_b32 v10, v4, 5, v10
	v_readlane_b32 s3, v251, 55
	v_readlane_b32 s66, v250, 17
	s_movk_i32 s8, 0x47ff
	v_readlane_b32 s13, v251, 18
	v_readlane_b32 s65, v250, 9
	v_readlane_b32 s15, v252, 52
	v_readlane_b32 s23, v250, 20
	v_lshlrev_b32_e32 v9, 2, v5
	v_lshl_add_u64 v[4:5], s[2:3], 0, v[10:11]
	s_mov_b64 s[6:7], 0
	v_readlane_b32 s53, v252, 13
	v_readlane_b32 s54, v252, 14
	v_readlane_b32 s55, v252, 15
	v_readlane_b32 s56, v252, 16
	v_readlane_b32 s57, v252, 17
	v_readlane_b32 s58, v252, 18
	v_readlane_b32 s59, v252, 19
	v_readlane_b32 s67, v252, 27
	global_load_dwordx4 v[44:47], v[2:3], off
	global_load_dwordx4 v[48:51], v[2:3], off offset:16
	global_load_dwordx4 v[52:55], v[2:3], off offset:32
	global_load_dwordx4 v[56:59], v[2:3], off offset:48
	global_load_dwordx4 v[60:63], v[4:5], off
	global_load_dwordx4 v[64:67], v[4:5], off offset:16
	s_waitcnt vmcnt(0)
.LBB0_214:
	s_waitcnt vmcnt(2)
	v_lshlrev_b32_e32 v18, 16, v60
	v_and_b32_e32 v34, 0xffff0000, v60
	v_lshlrev_b32_e32 v35, 16, v61
	v_and_b32_e32 v36, 0xffff0000, v61
	v_lshlrev_b32_e32 v37, 16, v62
	v_and_b32_e32 v38, 0xffff0000, v62
	v_lshlrev_b32_e32 v39, 16, v63
	v_and_b32_e32 v40, 0xffff0000, v63
	v_lshlrev_b32_e32 v27, 16, v64
	v_and_b32_e32 v26, 0xffff0000, v64
	v_lshlrev_b32_e32 v29, 16, v65
	v_and_b32_e32 v28, 0xffff0000, v65
	v_lshlrev_b32_e32 v31, 16, v66
	v_and_b32_e32 v30, 0xffff0000, v66
	v_lshlrev_b32_e32 v33, 16, v67
	v_and_b32_e32 v32, 0xffff0000, v67
	v_mov_b32_e32 v68, v4
	v_mov_b32_e32 v69, v5
	v_add_u32_e32 v6, s88, v6
	v_lshl_add_u64 v[4:5], v[4:5], 0, s[26:27]
	v_cmp_lt_i32_e32 vcc, s8, v6
	s_or_b64 s[6:7], vcc, s[6:7]
	global_load_dwordx4 v[60:63], v[4:5], off
	global_load_dwordx4 v[64:67], v[4:5], off offset:16
	v_mul_f32_e32 v16, v34, v34
	v_fmac_f32_e32 v16, v18, v18
	v_fmac_f32_e32 v16, v35, v35
	v_fmac_f32_e32 v16, v36, v36
	v_fmac_f32_e32 v16, v37, v37
	v_fmac_f32_e32 v16, v38, v38
	v_fmac_f32_e32 v16, v39, v39
	v_fmac_f32_e32 v16, v40, v40
	v_pk_mul_f32 v[14:15], v[26:27], v[26:27]
	s_nop 0
	v_add_f32_e32 v10, v15, v16
	v_add_f32_e32 v14, v14, v10
	v_pk_mul_f32 v[10:11], v[28:29], v[28:29]
	s_nop 0
	v_add_f32_e32 v11, v11, v14
	v_add_f32_e32 v14, v10, v11
	v_pk_mul_f32 v[10:11], v[30:31], v[30:31]
	s_nop 0
	v_add_f32_e32 v11, v11, v14
	v_add_f32_e32 v12, v10, v11
	v_pk_mul_f32 v[10:11], v[32:33], v[32:33]
	s_nop 0
	v_add_f32_e32 v11, v11, v12
	v_add_f32_e32 v10, v10, v11
	ds_bpermute_b32 v11, v7, v10
	s_waitcnt lgkmcnt(0)
	v_add_f32_e32 v10, v10, v11
	ds_bpermute_b32 v11, v8, v10
	s_waitcnt lgkmcnt(0)
	v_add_f32_e32 v10, v10, v11
	ds_bpermute_b32 v11, v9, v10
	s_waitcnt lgkmcnt(0)
	v_add_f32_e32 v10, v10, v11
	v_fmamk_f32 v10, v10, 0x3c000000, v230
	v_cmp_gt_f32_e32 vcc, s70, v10
	v_mul_f32_e32 v11, 0x4b800000, v10
	s_nop 0
	v_cndmask_b32_e32 v10, v10, v11, vcc
	v_rsq_f32_e32 v10, v10
	s_nop 0
	v_mul_f32_e32 v11, 0x45800000, v10
	v_cndmask_b32_e32 v41, v10, v11, vcc
	v_mul_f32_e32 v18, v41, v18
	v_mul_f32_e32 v34, v41, v34
	v_mul_f32_e32 v35, v41, v35
	v_mul_f32_e32 v36, v41, v36
	v_mul_f32_e32 v37, v41, v37
	v_mul_f32_e32 v38, v41, v38
	v_mul_f32_e32 v39, v41, v39
	v_mul_f32_e32 v40, v41, v40
	v_mul_f32_e32 v27, v41, v27
	v_mul_f32_e32 v26, v41, v26
	v_mul_f32_e32 v29, v41, v29
	v_mul_f32_e32 v28, v41, v28
	v_mul_f32_e32 v31, v41, v31
	v_mul_f32_e32 v30, v41, v30
	v_mul_f32_e32 v33, v41, v33
	v_mul_f32_e32 v32, v41, v32
	v_mul_f32_e32 v18, v44, v18
	v_mul_f32_e32 v34, v45, v34
	v_mul_f32_e32 v35, v46, v35
	v_mul_f32_e32 v36, v47, v36
	v_mul_f32_e32 v37, v48, v37
	v_mul_f32_e32 v38, v49, v38
	v_mul_f32_e32 v39, v50, v39
	v_mul_f32_e32 v40, v51, v40
	v_mul_f32_e32 v27, v52, v27
	v_mul_f32_e32 v26, v53, v26
	v_mul_f32_e32 v29, v54, v29
	v_mul_f32_e32 v28, v55, v28
	v_mul_f32_e32 v31, v56, v31
	v_mul_f32_e32 v30, v57, v30
	v_mul_f32_e32 v33, v58, v33
	v_mul_f32_e32 v32, v59, v32
	v_cvt_pk_bf16_f32 v10, v18, v34
	v_cvt_pk_bf16_f32 v11, v35, v36
	v_cvt_pk_bf16_f32 v12, v37, v38
	v_cvt_pk_bf16_f32 v13, v39, v40
	v_cvt_pk_bf16_f32 v14, v27, v26
	v_cvt_pk_bf16_f32 v15, v29, v28
	v_cvt_pk_bf16_f32 v16, v31, v30
	v_cvt_pk_bf16_f32 v17, v33, v32
	global_store_dwordx4 v[68:69], v[10:13], off
	global_store_dwordx4 v[68:69], v[14:17], off offset:16
	s_andn2_b64 exec, exec, s[6:7]
	s_cbranch_execnz .LBB0_214
